# up/down epilogue scale prefetch issued at the unit-loop header (earlier), on top of v24
# speedup vs baseline: 1.0024x; 1.0024x over previous
.LBB0_842:
	s_lshl_b32 s98, s54, 10
	s_lshl_b32 s100, s87, 10
	v_lshlrev_b32_e32 v241, 5, v235
	v_lshlrev_b32_e32 v253, 5, v236
	s_add_u32 s98, s45, s98
	s_addc_u32 s99, s80, 0
	s_add_u32 s100, s81, s100
	s_addc_u32 s101, s82, 0
	global_load_dwordx4 v[222:225], v241, s[98:99] offset:16
	global_load_dwordx4 v[226:229], v241, s[98:99]
	global_load_dwordx4 v[230:233], v253, s[100:101] offset:16
	global_load_dwordx4 v[242:245], v253, s[100:101]
	global_load_dwordx4 v[246:249], v253, s[100:101] offset:528
	global_load_dwordx2 v[250:251], v253, s[100:101] offset:512
	global_load_dwordx2 v[254:255], v253, s[100:101] offset:520
	s_add_i32 s72, s72, 1
	s_mul_i32 s0, s72, s88
	s_mul_hi_u32 s1, s72, s64
	s_add_i32 s1, s1, s0
	s_mul_i32 s0, s72, s64
	s_add_u32 s50, s0, s33
	s_addc_u32 s51, s1, s89
	v_cmp_gt_i64_e32 vcc, s[50:51], v[216:217]
	v_cmp_lt_i64_e64 s[0:1], s[50:51], v[214:215]
	s_cbranch_vccnz .LBB0_844
	s_ashr_i32 s46, s50, 31
	s_lshr_b32 s46, s46, 29
	s_add_i32 s46, s50, s46
	s_ashr_i32 s47, s46, 3
	s_and_b32 s46, s46, -8
	s_sub_i32 s46, s50, s46
	s_cmp_lt_i32 s46, 0
	s_cselect_b32 s48, s68, 0x158
	s_mul_i32 s46, s46, s48
	s_add_i32 s46, s46, s47
	s_mul_hi_i32 s47, s46, 0x2fa0be83
	s_lshr_b32 s48, s47, 31
	s_ashr_i32 s47, s47, 7
	s_add_i32 s47, s47, s48
	s_lshl_b32 s48, s47, 3
	s_sub_i32 s49, 32, s48
	s_min_i32 s49, s49, 8
	s_abs_i32 s50, s49
	v_cvt_f32_u32_e32 v2, s50
	s_sub_i32 s52, 0, s50
	s_mulk_i32 s47, 0x2b0
	s_sub_i32 s47, s46, s47
	v_rcp_iflag_f32_e32 v2, v2
	s_abs_i32 s46, s47
	s_xor_b32 s51, s47, s49
	s_ashr_i32 s51, s51, 31
	v_mul_f32_e32 v2, 0x4f7ffffe, v2
	v_cvt_u32_f32_e32 v2, v2
	s_nop 0
	v_readfirstlane_b32 s53, v2
	s_mul_i32 s52, s52, s53
	s_mul_hi_u32 s52, s53, s52
	s_add_i32 s53, s53, s52
	s_mul_hi_u32 s52, s46, s53
	s_mul_i32 s53, s52, s50
	s_sub_i32 s46, s46, s53
	s_add_i32 s58, s52, 1
	s_sub_i32 s53, s46, s50
	s_cmp_ge_u32 s46, s50
	s_cselect_b32 s52, s58, s52
	s_cselect_b32 s46, s53, s46
	s_add_i32 s53, s52, 1
	s_cmp_ge_u32 s46, s50
	s_cselect_b32 s46, s53, s52
	s_xor_b32 s46, s46, s51
	s_sub_i32 s46, s46, s51
	s_mul_i32 s49, s46, s49
	s_sub_i32 s47, s47, s49
	s_add_i32 s48, s48, s47

.LBB0_1088:
	s_lshl_b32 s98, s69, 8
	s_or_b32 s98, s98, s53
	s_lshl_b32 s99, s68, 8
	s_add_i32 s99, s99, s52
	v_lshl_add_u32 v235, v165, 3, s98
	v_add_u32_e32 v253, s99, v164
	v_lshlrev_b32_e32 v235, 2, v235
	v_lshlrev_b32_e32 v253, 2, v253
	global_load_dwordx4 v[226:229], v235, s[4:5] offset:16
	global_load_dwordx4 v[230:233], v235, s[4:5]
	global_load_dwordx4 v[236:239], v235, s[4:5] offset:528
	global_load_dwordx4 v[240:243], v235, s[4:5] offset:512
	global_load_dword v244, v253, s[12:13]
	global_load_dword v245, v253, s[12:13] offset:64
	global_load_dword v246, v253, s[12:13] offset:128
	global_load_dword v247, v253, s[12:13] offset:192
	global_load_dword v248, v253, s[12:13] offset:512
	global_load_dword v249, v253, s[12:13] offset:576
	global_load_dword v250, v253, s[12:13] offset:640
	global_load_dword v251, v253, s[12:13] offset:704
	s_add_i32 s51, s51, 1
	s_mul_i32 s0, s51, s88
	s_mul_hi_u32 s1, s51, s64
	s_add_i32 s1, s1, s0
	s_mul_i32 s0, s51, s64
	v_readlane_b32 s2, v252, 2
	s_add_u32 s0, s0, s2
	s_addc_u32 s1, s1, s89
	v_cmp_gt_i64_e32 vcc, s[0:1], v[160:161]
	v_cmp_lt_i64_e64 s[2:3], s[0:1], v[158:159]
	s_cbranch_vccnz .LBB0_1094
	s_ashr_i32 s1, s0, 31
	s_lshr_b32 s1, s1, 29
	s_add_i32 s26, s0, s1
	s_and_b32 s1, s26, -8
	s_sub_i32 s27, s0, s1
	s_cmp_gt_i32 s27, -1
	s_mov_b64 s[0:1], -1
	s_cbranch_scc0 .LBB0_1091
	s_lshl_b32 s34, s27, 6
	s_mov_b64 s[0:1], 0

.LBB0_1694:
	s_lshl_b32 s98, s54, 10
	s_lshl_b32 s100, s86, 10
	v_lshlrev_b32_e32 v241, 5, v235
	v_lshlrev_b32_e32 v253, 5, v236
	s_add_u32 s98, s45, s98
	s_addc_u32 s99, s79, 0
	s_add_u32 s100, s80, s100
	s_addc_u32 s101, s81, 0
	global_load_dwordx4 v[222:225], v241, s[98:99] offset:16
	global_load_dwordx4 v[226:229], v241, s[98:99]
	global_load_dwordx4 v[230:233], v253, s[100:101] offset:16
	global_load_dwordx4 v[242:245], v253, s[100:101]
	global_load_dwordx4 v[246:249], v253, s[100:101] offset:528
	global_load_dwordx2 v[250:251], v253, s[100:101] offset:512
	global_load_dwordx2 v[254:255], v253, s[100:101] offset:520
	s_add_i32 s71, s71, 1
	s_mul_i32 s0, s71, s96
	s_mul_hi_u32 s1, s71, s64
	s_add_i32 s1, s1, s0
	s_mul_i32 s0, s71, s64
	v_readlane_b32 s33, v252, 2
	s_add_u32 s50, s0, s33
	s_addc_u32 s51, s1, s87
	v_cmp_gt_i64_e32 vcc, s[50:51], v[216:217]
	v_cmp_lt_i64_e64 s[0:1], s[50:51], v[214:215]
	s_cbranch_vccnz .LBB0_1696
	s_ashr_i32 s43, s50, 31
	s_lshr_b32 s43, s43, 29
	s_add_i32 s43, s50, s43
	s_ashr_i32 s46, s43, 3
	s_and_b32 s43, s43, -8
	s_sub_i32 s43, s50, s43
	s_cmp_lt_i32 s43, 0
	s_cselect_b32 s47, s67, 0x158
	s_mul_i32 s43, s43, s47
	s_add_i32 s43, s43, s46
	s_mul_hi_i32 s46, s43, 0x2fa0be83
	s_lshr_b32 s47, s46, 31
	s_ashr_i32 s46, s46, 7
	s_add_i32 s46, s46, s47
	s_lshl_b32 s47, s46, 3
	s_sub_i32 s48, 32, s47
	s_min_i32 s48, s48, 8
	s_abs_i32 s49, s48
	v_cvt_f32_u32_e32 v2, s49
	s_sub_i32 s51, 0, s49
	s_mulk_i32 s46, 0x2b0
	s_sub_i32 s43, s43, s46
	v_rcp_iflag_f32_e32 v2, v2
	s_abs_i32 s46, s43
	s_xor_b32 s50, s43, s48
	s_ashr_i32 s50, s50, 31
	v_mul_f32_e32 v2, 0x4f7ffffe, v2
	v_cvt_u32_f32_e32 v2, v2
	s_nop 0
	v_readfirstlane_b32 s52, v2
	s_mul_i32 s51, s51, s52
	s_mul_hi_u32 s51, s52, s51
	s_add_i32 s52, s52, s51
	s_mul_hi_u32 s51, s46, s52
	s_mul_i32 s52, s51, s49
	s_sub_i32 s46, s46, s52
	s_add_i32 s53, s51, 1
	s_sub_i32 s52, s46, s49
	s_cmp_ge_u32 s46, s49
	s_cselect_b32 s51, s53, s51
	s_cselect_b32 s46, s52, s46
	s_add_i32 s52, s51, 1
	s_cmp_ge_u32 s46, s49
	s_cselect_b32 s46, s52, s51
	s_xor_b32 s46, s46, s50
	s_sub_i32 s46, s46, s50
	s_mul_i32 s48, s46, s48
	s_sub_i32 s43, s43, s48
	s_add_i32 s48, s47, s43

.LBB0_1940:
	s_lshl_b32 s98, s74, 8
	s_or_b32 s98, s98, s58
	s_lshl_b32 s99, s73, 8
	s_add_i32 s99, s99, s57
	v_lshl_add_u32 v235, v165, 3, s98
	v_add_u32_e32 v253, s99, v164
	v_lshlrev_b32_e32 v235, 2, v235
	v_lshlrev_b32_e32 v253, 2, v253
	global_load_dwordx4 v[226:229], v235, s[4:5] offset:16
	global_load_dwordx4 v[230:233], v235, s[4:5]
	global_load_dwordx4 v[236:239], v235, s[4:5] offset:528
	global_load_dwordx4 v[240:243], v235, s[4:5] offset:512
	global_load_dword v244, v253, s[12:13]
	global_load_dword v245, v253, s[12:13] offset:64
	global_load_dword v246, v253, s[12:13] offset:128
	global_load_dword v247, v253, s[12:13] offset:192
	global_load_dword v248, v253, s[12:13] offset:512
	global_load_dword v249, v253, s[12:13] offset:576
	global_load_dword v250, v253, s[12:13] offset:640
	global_load_dword v251, v253, s[12:13] offset:704
	s_add_i32 s56, s56, 1
	s_mul_i32 s0, s56, s96
	s_mul_hi_u32 s1, s56, s64
	s_add_i32 s1, s1, s0
	s_mul_i32 s0, s56, s64
	v_readlane_b32 s2, v252, 2
	s_add_u32 s0, s0, s2
	s_addc_u32 s1, s1, s87
	v_cmp_gt_i64_e32 vcc, s[0:1], v[160:161]
	v_cmp_lt_i64_e64 s[2:3], s[0:1], v[158:159]
	s_cbranch_vccnz .LBB0_1946
	s_ashr_i32 s1, s0, 31
	s_lshr_b32 s1, s1, 29
	s_add_i32 s34, s0, s1
	s_and_b32 s1, s34, -8
	s_sub_i32 s35, s0, s1
	s_cmp_gt_i32 s35, -1
	s_mov_b64 s[0:1], -1
	s_cbranch_scc0 .LBB0_1943
	s_lshl_b32 s44, s35, 6
	s_mov_b64 s[0:1], 0
